# adds batched K reads in boundary-tile QK and scalar v_mul for the o-rescale (was v_pk_mul) on top of v20
# speedup vs baseline: 1.0164x; 1.0008x over previous
.LBB0_162:
	v_add_u32_e32 v102, s15, v231
	ds_read_b128 v[22:25], v102
	ds_read_b128 v[26:29], v102 offset:32
	ds_read_b128 v[240:243], v102 offset:64
	ds_read_b128 v[244:247], v102 offset:96
	ds_read_b128 v[248:251], v102 offset:128
	ds_read_b128 v[130:133], v102 offset:160
	ds_read_b128 v[134:137], v102 offset:192
	ds_read_b128 v[104:107], v102 offset:224
	s_mul_i32 s14, s9, 0x5000
	s_addk_i32 s14, 0x3800
	s_cmp_lg_u32 s9, 0
	s_cselect_b32 s9, s14, 0x12800
	v_add_u32_e32 v233, s9, v232
	s_lshr_b32 s9, s5, 8
	v_lshrrev_b32_e32 v234, s9, v217
	v_and_b32_e32 v234, 1, v234
	v_cmp_eq_u32_e32 vcc, 1, v234
	s_add_i32 s5, s5, 64
	s_cmp_lg_u32 s4, s8
	v_cndmask_b32_e32 v234, v16, v14, vcc
	v_cndmask_b32_e64 v234, v234, v32, s[6:7]
	s_waitcnt lgkmcnt(7)
	v_mfma_f32_32x32x16_bf16 v[114:129], v[22:25], v[162:165], 0
	ds_read_b128 v[98:101], v102 offset:8704
	s_waitcnt lgkmcnt(7)
	v_mfma_f32_32x32x16_bf16 v[114:129], v[26:29], v[166:169], v[114:129]
	ds_read_b128 v[158:161], v102 offset:8736
	s_waitcnt lgkmcnt(7)
	v_mfma_f32_32x32x16_bf16 v[114:129], v[240:243], v[170:173], v[114:129]
	ds_read_b128 v[236:239], v102 offset:8768
	s_waitcnt lgkmcnt(7)
	v_mfma_f32_32x32x16_bf16 v[114:129], v[244:247], v[174:177], v[114:129]
	ds_read_b128 v[154:157], v102 offset:8800
	s_waitcnt lgkmcnt(7)
	v_mfma_f32_32x32x16_bf16 v[114:129], v[248:251], v[178:181], v[114:129]
	ds_read_b128 v[150:153], v102 offset:8832
	s_waitcnt lgkmcnt(7)
	v_mfma_f32_32x32x16_bf16 v[114:129], v[130:133], v[182:185], v[114:129]
	ds_read_b128 v[146:149], v102 offset:8864
	s_waitcnt lgkmcnt(7)
	v_mfma_f32_32x32x16_bf16 v[114:129], v[134:137], v[186:189], v[114:129]
	ds_read_b128 v[142:145], v102 offset:8896
	s_waitcnt lgkmcnt(7)
	v_mfma_f32_32x32x16_bf16 v[114:129], v[104:107], v[190:193], v[114:129]
	ds_read_b128 v[138:141], v102 offset:8928
	s_waitcnt lgkmcnt(7)
	v_mfma_f32_32x32x16_bf16 v[98:113], v[98:101], v[162:165], 0
	s_waitcnt lgkmcnt(6)
	v_mfma_f32_32x32x16_bf16 v[98:113], v[158:161], v[166:169], v[98:113]
	s_waitcnt lgkmcnt(5)
	v_mfma_f32_32x32x16_bf16 v[98:113], v[236:239], v[170:173], v[98:113]
	s_waitcnt lgkmcnt(4)
	v_mfma_f32_32x32x16_bf16 v[98:113], v[154:157], v[174:177], v[98:113]
	s_waitcnt lgkmcnt(3)
	v_mfma_f32_32x32x16_bf16 v[98:113], v[150:153], v[178:181], v[98:113]
	s_waitcnt lgkmcnt(2)
	v_mfma_f32_32x32x16_bf16 v[98:113], v[146:149], v[182:185], v[98:113]
	s_waitcnt lgkmcnt(1)
	v_mfma_f32_32x32x16_bf16 v[98:113], v[142:145], v[186:189], v[98:113]
	ds_read_b64_tr_b16 v[134:135], v233
	ds_read_b64_tr_b16 v[26:27], v233 offset:64
	ds_read_b64_tr_b16 v[130:131], v233 offset:128
	ds_read_b64_tr_b16 v[22:23], v233 offset:192
	ds_read_b64_tr_b16 v[136:137], v233 offset:2560
	ds_read_b64_tr_b16 v[28:29], v233 offset:2624
	ds_read_b64_tr_b16 v[132:133], v233 offset:2688
	ds_read_b128 v[240:243], v15
	ds_read_b128 v[248:251], v15 offset:32
	ds_read_b128 v[236:239], v15 offset:64
	ds_read_b128 v[154:157], v15 offset:96
	ds_read_b64_tr_b16 v[24:25], v233 offset:2752
	ds_read_b64_tr_b16 v[150:151], v233 offset:5120
	s_waitcnt lgkmcnt(13)
	v_mfma_f32_32x32x16_bf16 v[98:113], v[138:141], v[190:193], v[98:113]
	ds_read_b128 v[244:247], v15 offset:128
	ds_read_b128 v[158:161], v15 offset:160
	s_waitcnt lgkmcnt(7)
	s_waitcnt lgkmcnt(6)
	v_mfma_f32_32x32x16_bf16 v[34:49], v[134:137], v[18:21], v[34:49]
	s_waitcnt lgkmcnt(5)
	s_waitcnt lgkmcnt(4)
	v_fma_f32 v240, v114, s66, -v240
	v_fma_f32 v241, v115, s66, -v241
	v_fma_f32 v242, v116, s66, -v242
	v_fma_f32 v243, v117, s66, -v243
	v_fma_f32 v248, v118, s66, -v248
	v_fma_f32 v249, v119, s66, -v249
	v_fma_f32 v250, v120, s66, -v250
	v_fma_f32 v251, v121, s66, -v251
	v_fma_f32 v236, v122, s66, -v236
	v_fma_f32 v237, v123, s66, -v237
	v_fma_f32 v238, v124, s66, -v238
	v_fma_f32 v239, v125, s66, -v239
	v_fma_f32 v154, v126, s66, -v154
	v_fma_f32 v155, v127, s66, -v155
	v_fma_f32 v156, v128, s66, -v156
	v_fma_f32 v157, v129, s66, -v157
	ds_read_b64_tr_b16 v[122:123], v233 offset:5184
	ds_read_b64_tr_b16 v[126:127], v233 offset:5248
	ds_read_b64_tr_b16 v[114:115], v233 offset:5312
	ds_read_b64_tr_b16 v[152:153], v233 offset:7680
	ds_read_b64_tr_b16 v[124:125], v233 offset:7744
	ds_read_b64_tr_b16 v[128:129], v233 offset:7808
	ds_read_b64_tr_b16 v[116:117], v233 offset:7872
	ds_read_b128 v[118:121], v15 offset:192
	ds_read_b128 v[142:145], v15 offset:224
	s_waitcnt lgkmcnt(10)
	v_fma_f32 v245, v99, s66, -v245
	s_waitcnt lgkmcnt(9)
	s_waitcnt lgkmcnt(1)
	v_fma_f32 v244, v98, s66, -v244
	v_fma_f32 v246, v100, s66, -v246
	v_fma_f32 v247, v101, s66, -v247
	v_mfma_f32_32x32x16_bf16 v[66:81], v[130:133], v[18:21], v[66:81]
	v_max_f32_e32 v100, v241, v245
	v_fma_f32 v158, v102, s66, -v158
	v_fma_f32 v159, v103, s66, -v159
	v_fma_f32 v254, v108, s66, -v120
	v_max3_f32 v100, v240, v244, v100
	v_max_f32_e32 v101, v242, v246
	v_mfma_f32_32x32x16_bf16 v[34:49], v[150:153], v[10:13], v[34:49]
	v_max_f32_e32 v108, v243, v247
	v_fma_f32 v160, v104, s66, -v160
	v_fma_f32 v161, v105, s66, -v161
	v_max3_f32 v100, v100, v101, v108
	v_max_f32_e32 v101, v248, v158
	v_max_f32_e32 v108, v249, v159
	v_fma_f32 v252, v106, s66, -v118
	v_fma_f32 v253, v107, s66, -v119
	v_max3_f32 v100, v100, v101, v108
	v_max_f32_e32 v101, v250, v160
	v_max_f32_e32 v108, v251, v161
	s_waitcnt lgkmcnt(0)
	v_fma_f32 v225, v109, s66, -v121
	v_max3_f32 v100, v100, v101, v108
	v_max_f32_e32 v101, v236, v252
	v_max_f32_e32 v108, v237, v253
	v_fma_f32 v226, v110, s66, -v142
	v_fma_f32 v210, v111, s66, -v143
	v_max3_f32 v100, v100, v101, v108
	v_max_f32_e32 v101, v238, v254
	v_max_f32_e32 v108, v239, v225
	ds_read_b64_tr_b16 v[138:139], v233 offset:10240
	ds_read_b64_tr_b16 v[142:143], v233 offset:10304
	ds_read_b64_tr_b16 v[146:147], v233 offset:10368
	v_fma_f32 v211, v112, s66, -v144
	v_fma_f32 v212, v113, s66, -v145
	v_max3_f32 v100, v100, v101, v108
	v_max_f32_e32 v101, v154, v226
	v_max_f32_e32 v108, v155, v210
	ds_read_b64_tr_b16 v[118:119], v233 offset:10432
	ds_read_b64_tr_b16 v[140:141], v233 offset:12800
	ds_read_b64_tr_b16 v[144:145], v233 offset:12864
	ds_read_b64_tr_b16 v[148:149], v233 offset:12928
	ds_read_b64_tr_b16 v[120:121], v233 offset:12992
	v_max3_f32 v100, v100, v101, v108
	v_max_f32_e32 v101, v156, v211
	v_max_f32_e32 v108, v157, v212
	ds_read_b64_tr_b16 v[104:105], v233 offset:17920
	v_mfma_f32_32x32x16_bf16 v[66:81], v[126:129], v[10:13], v[66:81]
	v_max3_f32 v126, v100, v101, v108
	ds_bpermute_b32 v127, v31, v126
	ds_read_b64_tr_b16 v[102:103], v233 offset:15360
	ds_read_b64_tr_b16 v[106:107], v233 offset:15424
	ds_read_b64_tr_b16 v[110:111], v233 offset:15488
	ds_read_b64_tr_b16 v[98:99], v233 offset:15552
	ds_read_b64_tr_b16 v[108:109], v233 offset:17984
	ds_read_b64_tr_b16 v[112:113], v233 offset:18048
	ds_read_b64_tr_b16 v[100:101], v233 offset:18112
	v_add_u32_e32 v15, 0x100, v15
	s_waitcnt lgkmcnt(7)
	v_max_f32_e32 v126, v126, v127
	v_add_f32_e32 v126, v126, v234
	v_max_f32_e32 v127, v235, v126
	v_mfma_f32_32x32x16_bf16 v[34:49], v[138:141], v[6:9], v[34:49]
	v_cmp_neq_f32_e32 vcc, s34, v127
	s_nop 1
	v_cndmask_b32_e32 v126, 0, v127, vcc
	v_sub_f32_e32 v131, v235, v126
	v_sub_f32_e32 v126, v126, v234
	v_mov_b32_e32 v234, v127
	v_sub_f32_e32 v127, v240, v126
	v_exp_f32_e32 v127, v127
	v_mfma_f32_32x32x16_bf16 v[82:97], v[26:29], v[18:21], v[82:97]
	v_sub_f32_e32 v26, v246, v126
	v_exp_f32_e32 v133, v26
	v_sub_f32_e32 v26, v243, v126
	v_exp_f32_e32 v134, v26
	v_sub_f32_e32 v26, v247, v126
	v_exp_f32_e32 v135, v26
	v_sub_f32_e32 v28, v159, v126
	s_waitcnt lgkmcnt(6)
	v_mfma_f32_32x32x16_bf16 v[34:49], v[102:105], v[2:5], v[34:49]
	v_sub_f32_e32 v102, v244, v126
	v_exp_f32_e32 v128, v102
	v_sub_f32_e32 v102, v241, v126
	v_exp_f32_e32 v129, v102
	v_sub_f32_e32 v102, v245, v126
	v_exp_f32_e32 v130, v102
	v_add_f32_e32 v102, v128, v127
	v_mfma_f32_32x32x16_bf16 v[82:97], v[122:125], v[10:13], v[82:97]
	v_add_f32_e32 v102, 0, v102
	v_add_f32_e32 v103, v130, v129
	v_add_f32_e32 v102, v103, v102
	v_sub_f32_e32 v103, v242, v126
	v_exp_f32_e32 v132, v103
	v_add_f32_e32 v27, v135, v134
	v_exp_f32_e32 v28, v28
	v_mfma_f32_32x32x16_bf16 v[66:81], v[146:149], v[6:9], v[66:81]
	v_add_f32_e32 v26, v133, v132
	v_add_f32_e32 v26, v26, v102
	v_sub_f32_e32 v102, v250, v126
	v_exp_f32_e32 v103, v102
	v_sub_f32_e32 v102, v160, v126
	v_exp_f32_e32 v105, v102
	v_sub_f32_e32 v102, v251, v126
	v_mfma_f32_32x32x16_bf16 v[82:97], v[142:145], v[6:9], v[82:97]
	v_sub_f32_e32 v104, v161, v126
	v_exp_f32_e32 v102, v102
	v_exp_f32_e32 v104, v104
	s_waitcnt lgkmcnt(1)
	v_mfma_f32_32x32x16_bf16 v[66:81], v[110:113], v[2:5], v[66:81]
	v_add_f32_e32 v110, v27, v26
	v_sub_f32_e32 v26, v248, v126
	v_exp_f32_e32 v27, v26
	v_sub_f32_e32 v26, v158, v126
	v_exp_f32_e32 v29, v26
	v_sub_f32_e32 v26, v249, v126
	v_exp_f32_e32 v26, v26
	v_mfma_f32_32x32x16_bf16 v[50:65], v[22:25], v[18:21], v[50:65]
	v_sub_f32_e32 v112, v225, v126
	v_exp_f32_e32 v112, v112
	v_sub_f32_e32 v18, v226, v126
	v_exp_f32_e32 v23, v18
	v_sub_f32_e32 v18, v155, v126
	v_mfma_f32_32x32x16_bf16 v[82:97], v[106:109], v[2:5], v[82:97]
	v_add_f32_e64 v106, v28, v26
	v_add_f32_e64 v107, v29, v27
	v_add_f32_e32 v107, v107, v110
	v_add_f32_e32 v108, v106, v107
	v_add_f32_e64 v106, v104, v102
	v_add_f32_e64 v107, v105, v103
	v_sub_f32_e32 v110, v238, v126
	v_add_f32_e32 v107, v107, v108
	v_mfma_f32_32x32x16_bf16 v[50:65], v[114:117], v[10:13], v[50:65]
	v_add_f32_e32 v124, v106, v107
	v_sub_f32_e32 v106, v236, v126
	v_exp_f32_e32 v107, v106
	v_sub_f32_e32 v106, v252, v126
	v_exp_f32_e32 v109, v106
	v_sub_f32_e32 v106, v237, v126
	v_sub_f32_e32 v108, v253, v126
	v_exp_f32_e32 v106, v106
	v_exp_f32_e32 v108, v108
	v_exp_f32_e32 v111, v110
	v_sub_f32_e32 v110, v254, v126
	v_exp_f32_e32 v113, v110
	v_sub_f32_e32 v110, v239, v126
	v_exp_f32_e32 v110, v110
	v_mfma_f32_32x32x16_bf16 v[50:65], v[118:121], v[6:9], v[50:65]
	v_add_f32_e64 v122, v108, v106
	v_add_f32_e64 v123, v109, v107
	v_sub_f32_e32 v10, v211, v126
	v_add_f32_e32 v123, v123, v124
	v_add_f32_e32 v124, v122, v123
	v_pk_add_f32 v[122:123], v[112:113], v[110:111]
	v_exp_f32_e32 v115, v10
	v_add_f32_e32 v123, v123, v124
	v_add_f32_e32 v124, v122, v123
	v_sub_f32_e32 v122, v154, v126
	v_exp_f32_e32 v123, v122
	v_exp_f32_e32 v122, v18
	v_sub_f32_e32 v18, v210, v126
	v_exp_f32_e32 v22, v18
	v_sub_f32_e32 v10, v157, v126
	v_sub_f32_e32 v18, v156, v126
	v_exp_f32_e32 v24, v10
	v_sub_f32_e32 v10, v212, v126
	s_waitcnt lgkmcnt(0)
	v_mfma_f32_32x32x16_bf16 v[50:65], v[98:101], v[2:5], v[50:65]
	v_exp_f32_e32 v25, v18
	v_exp_f32_e32 v114, v10
	v_pk_add_f32 v[6:7], v[22:23], v[122:123]
	v_exp_f32_e32 v116, v131
	v_add_f32_e32 v7, v7, v124
	v_add_f32_e32 v8, v6, v7
	v_pk_add_f32 v[6:7], v[114:115], v[24:25]
	v_mul_f32_e32 v48, v116, v48
	v_mul_f32_e32 v49, v116, v49
	v_add_f32_e32 v7, v7, v8
	v_add_f32_e32 v233, v6, v7
	v_fmac_f32_e32 v233, v33, v116
	v_mul_f32_e32 v46, v116, v46
	v_mul_f32_e32 v47, v116, v47
	v_mul_f32_e32 v44, v116, v44
	v_mul_f32_e32 v45, v116, v45
	v_mul_f32_e32 v42, v116, v42
	v_mul_f32_e32 v43, v116, v43
	v_mul_f32_e32 v40, v116, v40
	v_mul_f32_e32 v41, v116, v41
	v_mul_f32_e32 v38, v116, v38
	v_mul_f32_e32 v39, v116, v39
	v_mul_f32_e32 v36, v116, v36
	v_mul_f32_e32 v37, v116, v37
	v_mul_f32_e32 v34, v116, v34
	v_mul_f32_e32 v35, v116, v35
	v_mul_f32_e32 v96, v116, v96
	v_mul_f32_e32 v97, v116, v97
	v_mul_f32_e32 v94, v116, v94
	v_mul_f32_e32 v95, v116, v95
	v_mul_f32_e32 v92, v116, v92
	v_mul_f32_e32 v93, v116, v93
	v_mul_f32_e32 v90, v116, v90
	v_mul_f32_e32 v91, v116, v91
	v_mul_f32_e32 v88, v116, v88
	v_mul_f32_e32 v89, v116, v89
	v_mul_f32_e32 v86, v116, v86
	v_mul_f32_e32 v87, v116, v87
	v_mul_f32_e32 v84, v116, v84
	v_mul_f32_e32 v85, v116, v85
	v_mul_f32_e32 v82, v116, v82
	v_mul_f32_e32 v83, v116, v83
	v_mul_f32_e32 v80, v116, v80
	v_mul_f32_e32 v81, v116, v81
	v_mul_f32_e32 v78, v116, v78
	v_mul_f32_e32 v79, v116, v79
	v_mul_f32_e32 v76, v116, v76
	v_mul_f32_e32 v77, v116, v77
	v_mul_f32_e32 v74, v116, v74
	v_mul_f32_e32 v75, v116, v75
	v_mul_f32_e32 v72, v116, v72
	v_mul_f32_e32 v73, v116, v73
	v_mul_f32_e32 v70, v116, v70
	v_mul_f32_e32 v71, v116, v71
	v_mul_f32_e32 v68, v116, v68
	v_mul_f32_e32 v69, v116, v69
	v_mul_f32_e32 v66, v116, v66
	v_mul_f32_e32 v67, v116, v67
	v_mul_f32_e32 v64, v116, v64
	v_mul_f32_e32 v65, v116, v65
	v_mul_f32_e32 v62, v116, v62
	v_mul_f32_e32 v63, v116, v63
	v_mul_f32_e32 v60, v116, v60
	v_mul_f32_e32 v61, v116, v61
	v_mul_f32_e32 v58, v116, v58
	v_mul_f32_e32 v59, v116, v59
	v_mul_f32_e32 v56, v116, v56
	v_mul_f32_e32 v57, v116, v57
	v_mul_f32_e32 v54, v116, v54
	v_mul_f32_e32 v55, v116, v55
	v_mul_f32_e32 v52, v116, v52
	v_mul_f32_e32 v53, v116, v53
	v_mul_f32_e32 v50, v116, v50
	v_mul_f32_e32 v51, v116, v51
	v_cvt_pk_bf16_f32 v18, v127, v129
	v_cvt_pk_bf16_f32 v19, v132, v134
	v_cvt_pk_bf16_f32 v20, v27, v26
	v_cvt_pk_bf16_f32 v21, v103, v102
	v_cvt_pk_bf16_f32 v10, v107, v106
	v_cvt_pk_bf16_f32 v11, v111, v110
	v_cvt_pk_bf16_f32 v12, v123, v122
	v_cvt_pk_bf16_f32 v13, v25, v24
	v_cvt_pk_bf16_f32 v6, v128, v130
	v_cvt_pk_bf16_f32 v7, v133, v135
	v_cvt_pk_bf16_f32 v8, v29, v28
	v_cvt_pk_bf16_f32 v9, v105, v104
	v_cvt_pk_bf16_f32 v2, v109, v108
	v_cvt_pk_bf16_f32 v3, v113, v112
	v_cvt_pk_bf16_f32 v4, v23, v22
	v_cvt_pk_bf16_f32 v5, v115, v114
	s_barrier
	s_cbranch_scc0 .LBB0_167
	v_mov_b32_e32 v235, v234
	v_mov_b32_e32 v33, v233
	s_mov_b32 s9, s37
	s_mov_b32 s14, s8
	s_branch .LBB0_159

; #define LAS __attribute__((address_space(3)))
; __device__ __forceinline__ f32x16 mfma32(bf16x8 a, bf16x8 b, f32x16 c) { return __builtin_amdgcn_mfma_f32_32x32x16_bf16(a, b, c, 0, 0, 0); }
; __device__ __forceinline__ void attn_item(LAS unsigned char* lds, const bf16_t* Z, bf16_t* Y, const float* logf, const float* ksum, const float* rel_bias,
;                                           const int moba, const int b, const int h, const int qt) {
;     ...
;         if (k0 <= qmax_w) {
;             f32x16 s0 = zero16(), s1 = zero16();
; #pragma unroll
;             for (int kk = 0; kk < 8; ++kk) { const bf16x8 a0 = *(const LAS bf16x8*)(lds + kc + kroff + 32 * kk), a1 = *(const LAS bf16x8*)(lds + kc + kroff + 32 * KSTR + 32 * kk);
;                 s0 = mfma32(a0, qf[kk], s0); s1 = mfma32(a1, qf[kk], s1); }
;             if (!moba) {
; #pragma unroll
;                 for (int ig = 0; ig < 4; ++ig) { const f32x4 cb0 = *(const LAS f32x4*)(cbuf + k0 + 8 * ig + 4 * hh), cb1 = *(const LAS f32x4*)(cbuf + k0 + 32 + 8 * ig + 4 * hh);
; #pragma unroll
;                     for (int e = 0; e < 4; ++e) { s0[4 * ig + e] = __builtin_fmaf(s0[4 * ig + e], sc2, cq2 - cb0[e]); s1[4 * ig + e] = __builtin_fmaf(s1[4 * ig + e], sc2, cq2 - cb1[e]); } }
;                 if (k0 + 63 > qmin_w) {
; #pragma unroll
;                     for (int i = 0; i < 16; ++i) { const int key = k0 + (i & 3) + 8 * (i >> 2) + 4 * hh; if (key > qrow) s0[i] = -INFINITY; if (key + 32 > qrow) s1[i] = -INFINITY; }
;                 }
;             } else {
;                 const bool past = k0 < 256 * qt;
;                 if (past && (k0 + 63 + 113 <= qmin_w)) {
;                     const float bias = ((sel >> (k0 >> 8)) & 1u) ? lut[128] : -INFINITY;
.LBB0_172:
	s_cmp_gt_i32 s38, s23
	s_cbranch_scc1 .LBB0_189
	v_add_u32_e32 v17, s5, v231
	ds_read_b128 v[18:21], v17
	ds_read_b128 v[22:25], v17 offset:8704
	ds_read_b128 v[26:29], v17 offset:32
	ds_read_b128 v[114:117], v17 offset:8736
	ds_read_b128 v[118:121], v17 offset:64
	ds_read_b128 v[122:125], v17 offset:8768
	ds_read_b128 v[126:129], v17 offset:96
	ds_read_b128 v[146:149], v17 offset:8800
	ds_read_b128 v[150:153], v17 offset:128
	ds_read_b128 v[154:157], v17 offset:8832
	ds_read_b128 v[158:161], v17 offset:160
	s_mov_b64 s[4:5], -1
	s_and_b64 vcc, exec, s[12:13]
	s_waitcnt lgkmcnt(10)
	v_mfma_f32_32x32x16_bf16 v[130:145], v[18:21], v[162:165], 0
	ds_read_b128 v[18:21], v17 offset:8864
	s_waitcnt lgkmcnt(10)
	v_mfma_f32_32x32x16_bf16 v[98:113], v[22:25], v[162:165], 0
	ds_read_b128 v[22:25], v17 offset:192
	s_waitcnt lgkmcnt(10)
	v_mfma_f32_32x32x16_bf16 v[130:145], v[26:29], v[166:169], v[130:145]
	ds_read_b128 v[26:29], v17 offset:8896
	s_waitcnt lgkmcnt(10)
	v_mfma_f32_32x32x16_bf16 v[98:113], v[114:117], v[166:169], v[98:113]
	ds_read_b128 v[114:117], v17 offset:224
	s_waitcnt lgkmcnt(10)
	v_mfma_f32_32x32x16_bf16 v[130:145], v[118:121], v[170:173], v[130:145]
	ds_read_b128 v[118:121], v17 offset:8928
	s_waitcnt lgkmcnt(10)
	v_mfma_f32_32x32x16_bf16 v[98:113], v[122:125], v[170:173], v[98:113]
	s_waitcnt lgkmcnt(9)
	v_mfma_f32_32x32x16_bf16 v[130:145], v[126:129], v[174:177], v[130:145]
	s_waitcnt lgkmcnt(8)
	v_mfma_f32_32x32x16_bf16 v[98:113], v[146:149], v[174:177], v[98:113]
	s_waitcnt lgkmcnt(7)
	v_mfma_f32_32x32x16_bf16 v[130:145], v[150:153], v[178:181], v[130:145]
	s_waitcnt lgkmcnt(6)
	v_mfma_f32_32x32x16_bf16 v[98:113], v[154:157], v[178:181], v[98:113]
	s_waitcnt lgkmcnt(5)
	v_mfma_f32_32x32x16_bf16 v[130:145], v[158:161], v[182:185], v[130:145]
	s_waitcnt lgkmcnt(4)
	v_mfma_f32_32x32x16_bf16 v[98:113], v[18:21], v[182:185], v[98:113]
	s_waitcnt lgkmcnt(3)
	v_mfma_f32_32x32x16_bf16 v[130:145], v[22:25], v[186:189], v[130:145]
	s_waitcnt lgkmcnt(2)
	v_mfma_f32_32x32x16_bf16 v[98:113], v[26:29], v[186:189], v[98:113]
	s_waitcnt lgkmcnt(1)
	v_mfma_f32_32x32x16_bf16 v[130:145], v[114:117], v[190:193], v[130:145]
	s_waitcnt lgkmcnt(0)
	v_mfma_f32_32x32x16_bf16 v[98:113], v[118:121], v[190:193], v[98:113]
	s_cbranch_vccz .LBB0_185
	s_cmp_lt_u32 s38, s54
	s_cselect_b64 s[16:17], -1, 0
	s_cmp_ge_u32 s38, s54
	s_cselect_b64 s[4:5], -1, 0
	s_add_i32 s8, s38, 0xb0
	s_cmp_gt_i32 s8, s68
	s_cselect_b64 s[18:19], -1, 0
	s_or_b64 s[4:5], s[4:5], s[18:19]
	s_andn2_b64 vcc, exec, s[4:5]
	s_mov_b64 s[4:5], -1
	s_cbranch_vccz .LBB0_179
	s_lshr_b32 s4, s38, 8
	v_lshrrev_b32_e32 v17, s4, v217
	v_and_b32_e32 v17, 1, v17
	v_cmp_eq_u32_e32 vcc, 1, v17
	v_mov_b32_e32 v18, 0xff800000
	s_and_saveexec_b64 s[4:5], vcc
	s_cbranch_execz .LBB0_177
	v_readlane_b32 s8, v255, 39
	s_nop 1
	v_mov_b32_e32 v17, s8
	ds_read_b32 v18, v17
